# v61 + layer-1 W_in weight transposes moved out of the prologue into the idle tail of layer 0's mixer phase (non-chain workgroups, atomic item queue)
# baseline (speedup 1.0000x reference)
; #define GAS __attribute__((address_space(1)))
; __device__ __forceinline__ unsigned cvt_pk_bf16(float lo, float hi) { const f32x2 v = {lo, hi}; return __builtin_bit_cast(unsigned, __builtin_convertvector(v, bf16n2)); }
;     __device__ __forceinline__ int lane_() const { return lane_id(); }
; #define F_w_in F.in(8)
; __device__ __forceinline__ void p0_transpose_item(const GAS float* W, int K, int N, GAS bf16* WT, int item, int lane) {
;     const int nblk = N / 64, kb = item / nblk, nb = item - kb * nblk, r = lane >> 4, c4 = lane & 15;
;     const GAS float* src = W + (size_t)(64 * kb + 16 * r) * N + 64 * nb + 4 * c4;
;     f32x4 v[16];
; #pragma unroll
;     for (int i = 0; i < 16; ++i) v[i] = __builtin_nontemporal_load((const GAS f32x4*)(src + (size_t)i * N));
;     GAS bf16* dst = WT + (size_t)(64 * nb + 4 * c4) * K + 64 * kb + 16 * r;
; #pragma unroll
;     for (int j = 0; j < 4; ++j) { v4u a, b;
;         a.x = cvt_pk_bf16(v[0][j], v[1][j]); a.y = cvt_pk_bf16(v[2][j], v[3][j]); a.z = cvt_pk_bf16(v[4][j], v[5][j]); a.w = cvt_pk_bf16(v[6][j], v[7][j]);
;         b.x = cvt_pk_bf16(v[8][j], v[9][j]); b.y = cvt_pk_bf16(v[10][j], v[11][j]); b.z = cvt_pk_bf16(v[12][j], v[13][j]); b.w = cvt_pk_bf16(v[14][j], v[15][j]);
;         *(GAS v4u*)(dst + (size_t)j * K) = a; *(GAS v4u*)(dst + (size_t)j * K + 8) = b; }
; }
; __device__ __forceinline__ void phase_prologue(Frame& F) {
;     ...
;     for (int it = gw; it < NITEMS; it += NGW) {
;         int r = it;
;         if (r < 2 * I_IN) { const int l = r / I_IN; p0_transpose_item(F_w_in + (size_t)l * D * NPROJ, D, NPROJ, win_t + (size_t)l * NPROJ * D, r % I_IN, F.lane_()); continue; } r -= 2 * I_IN;
.LBB0_27:
	s_andn2_b64 vcc, exec, s[10:11]
	s_cbranch_vccnz .LBB0_16
	s_cmpk_gt_i32 s59, 0xcff
	s_cbranch_scc1 .LBB0_16
	v_mov_b32_e32 v0, s44
	ds_read_b64 v[2:3], v0
	s_mul_hi_i32 s8, s59, 0x4ec4ec4f
	s_lshr_b32 s10, s8, 31
	s_ashr_i32 s8, s8, 10
	s_add_i32 s8, s8, s10
	s_waitcnt lgkmcnt(0)
	v_readfirstlane_b32 s11, v2
	s_mul_i32 s13, s8, 0x3400000
	v_readfirstlane_b32 s10, v3
	s_mul_hi_i32 s12, s8, 0x3400000
	s_add_u32 s14, s11, s13
	s_addc_u32 s15, s10, s12
	s_mul_i32 s10, s8, 0x1a00000
	s_mul_hi_i32 s11, s8, 0x1a00000
	s_add_u32 s10, s1, s10
	s_mulk_i32 s8, 0xf300
	s_addc_u32 s11, s7, s11
	s_add_i32 s8, s59, s8
	v_mov_b32_e32 v0, 0
	s_mul_i32 s12, s8, 0x4ec5
	v_mbcnt_lo_u32_b32 v0, -1, v0
	s_lshr_b32 s13, s12, 31
	s_ashr_i32 s12, s12, 22
	v_mbcnt_hi_u32_b32 v0, -1, v0
	s_add_i32 s12, s12, s13
	s_mul_i32 s13, s12, 0xffffff30
	s_lshl_b32 s12, s12, 6
	v_and_b32_e32 v68, -16, v0
	v_add_u32_e32 v4, s12, v68
	v_mov_b64_e32 v[2:3], s[14:15]
	s_add_i32 s8, s8, s13
	v_mad_i64_i32 v[2:3], s[14:15], v4, s40, v[2:3]
	s_lshl_b32 s14, s8, 6
	v_lshlrev_b32_e32 v0, 2, v0
	s_ashr_i32 s15, s14, 31
	v_and_b32_e32 v69, 60, v0
	v_lshl_add_u64 v[2:3], s[14:15], 2, v[2:3]
	v_lshlrev_b32_e32 v0, 2, v69
	v_lshl_add_u64 v[42:43], v[2:3], 0, v[0:1]
	v_add_co_u32_e32 v6, vcc, s40, v42
	s_ashr_i32 s13, s12, 31
	s_nop 0
	v_addc_co_u32_e32 v7, vcc, 0, v43, vcc
	v_add_co_u32_e32 v10, vcc, s45, v42
	global_load_dwordx4 v[2:5], v[42:43], off nt
	s_nop 0
	global_load_dwordx4 v[6:9], v[6:7], off nt
	v_addc_co_u32_e32 v11, vcc, 0, v43, vcc
	v_add_co_u32_e32 v14, vcc, s46, v42
	s_waitcnt vmcnt(0)
	v_cvt_pk_bf16_f32 v66, v4, v8
	v_addc_co_u32_e32 v15, vcc, 0, v43, vcc
	v_add_co_u32_e32 v18, vcc, s47, v42
	global_load_dwordx4 v[10:13], v[10:11], off nt
	s_nop 0
	global_load_dwordx4 v[14:17], v[14:15], off nt
	v_addc_co_u32_e32 v19, vcc, 0, v43, vcc
	v_add_co_u32_e32 v22, vcc, s48, v42
	v_or_b32_e32 v4, s14, v69
	s_nop 0
	v_addc_co_u32_e32 v23, vcc, 0, v43, vcc
	v_add_co_u32_e32 v26, vcc, s49, v42
	global_load_dwordx4 v[18:21], v[18:19], off nt
	s_nop 0
	global_load_dwordx4 v[22:25], v[22:23], off nt
	v_addc_co_u32_e32 v27, vcc, 0, v43, vcc
	v_add_co_u32_e32 v30, vcc, s50, v42
	v_cvt_pk_bf16_f32 v70, v5, v9
	s_nop 0
	v_addc_co_u32_e32 v31, vcc, 0, v43, vcc
	v_add_co_u32_e32 v34, vcc, s51, v42
	global_load_dwordx4 v[26:29], v[26:27], off nt
	s_nop 0
	global_load_dwordx4 v[30:33], v[30:31], off nt
	v_addc_co_u32_e32 v35, vcc, 0, v43, vcc
	v_add_co_u32_e32 v38, vcc, s52, v42
	v_ashrrev_i32_e32 v5, 31, v4
	s_nop 0
	v_addc_co_u32_e32 v39, vcc, 0, v43, vcc
	v_add_co_u32_e32 v44, vcc, s53, v42
	global_load_dwordx4 v[34:37], v[34:35], off nt
	s_nop 0
	global_load_dwordx4 v[38:41], v[38:39], off nt
	v_addc_co_u32_e32 v45, vcc, 0, v43, vcc
	v_add_co_u32_e32 v46, vcc, s54, v42
	v_lshlrev_b64 v[4:5], 11, v[4:5]
	s_nop 0
	v_addc_co_u32_e32 v47, vcc, 0, v43, vcc
	v_add_co_u32_e32 v50, vcc, s55, v42
	v_lshl_add_u64 v[4:5], s[10:11], 0, v[4:5]
	s_nop 0
	v_addc_co_u32_e32 v51, vcc, 0, v43, vcc
	v_add_co_u32_e32 v54, vcc, s56, v42
	v_lshl_add_u64 v[4:5], s[12:13], 1, v[4:5]
	s_nop 0
	v_addc_co_u32_e32 v55, vcc, 0, v43, vcc
	v_add_co_u32_e32 v58, vcc, s57, v42
	v_ashrrev_i32_e32 v69, 31, v68
	s_nop 0
	v_addc_co_u32_e32 v59, vcc, 0, v43, vcc
	v_add_co_u32_e32 v62, vcc, s58, v42
	v_cvt_pk_bf16_f32 v2, v2, v6
	s_nop 0
	v_addc_co_u32_e32 v63, vcc, 0, v43, vcc
	global_load_dwordx4 v[42:45], v[44:45], off nt
	s_nop 0
	global_load_dwordx4 v[46:49], v[46:47], off nt
	s_nop 0
	global_load_dwordx4 v[50:53], v[50:51], off nt
	s_nop 0
	global_load_dwordx4 v[54:57], v[54:55], off nt
	s_nop 0
	global_load_dwordx4 v[58:61], v[58:59], off nt
	s_nop 0
	global_load_dwordx4 v[62:65], v[62:63], off nt
	v_cvt_pk_bf16_f32 v6, v3, v7
	s_waitcnt vmcnt(12)
	v_cvt_pk_bf16_f32 v3, v10, v14
	v_cvt_pk_bf16_f32 v7, v11, v15
	v_lshl_add_u64 v[10:11], v[68:69], 1, v[4:5]
	v_cvt_pk_bf16_f32 v67, v12, v16
	v_cvt_pk_bf16_f32 v71, v13, v17
	s_waitcnt vmcnt(10)
	v_cvt_pk_bf16_f32 v4, v18, v22
	v_cvt_pk_bf16_f32 v8, v19, v23
	v_cvt_pk_bf16_f32 v68, v20, v24
	v_cvt_pk_bf16_f32 v72, v21, v25
	s_waitcnt vmcnt(8)
	v_cvt_pk_bf16_f32 v5, v26, v30
	global_store_dwordx4 v[10:11], v[2:5], off
	v_cvt_pk_bf16_f32 v9, v27, v31
	global_store_dwordx4 v[10:11], v[6:9], off offset:2048
	v_cvt_pk_bf16_f32 v69, v28, v32
	v_cvt_pk_bf16_f32 v73, v29, v33
	v_add_co_u32_e32 v6, vcc, s27, v10
	s_waitcnt vmcnt(8)
	v_cvt_pk_bf16_f32 v2, v34, v38
	v_addc_co_u32_e32 v7, vcc, 0, v11, vcc
	global_store_dwordx4 v[6:7], v[66:69], off
	s_waitcnt vmcnt(7)
	v_cvt_pk_bf16_f32 v3, v42, v46
	s_waitcnt vmcnt(5)
	v_cvt_pk_bf16_f32 v4, v50, v54
	s_waitcnt vmcnt(3)
	v_cvt_pk_bf16_f32 v5, v58, v62
	global_store_dwordx4 v[10:11], v[2:5], off offset:16
	s_nop 1
	v_cvt_pk_bf16_f32 v2, v35, v39
	v_cvt_pk_bf16_f32 v3, v43, v47
	v_cvt_pk_bf16_f32 v4, v51, v55
	v_cvt_pk_bf16_f32 v5, v59, v63
	global_store_dwordx4 v[10:11], v[2:5], off offset:2064
	s_nop 1
	v_cvt_pk_bf16_f32 v2, v36, v40
	v_cvt_pk_bf16_f32 v3, v44, v48
	v_cvt_pk_bf16_f32 v4, v52, v56
	v_cvt_pk_bf16_f32 v5, v60, v64
	global_store_dwordx4 v[6:7], v[2:5], off offset:16
	s_nop 1
	v_cvt_pk_bf16_f32 v2, v37, v41
	v_cvt_pk_bf16_f32 v3, v45, v49
	v_cvt_pk_bf16_f32 v4, v53, v57
	v_cvt_pk_bf16_f32 v5, v61, v65
	global_store_dwordx4 v[6:7], v[70:73], off offset:2048
	global_store_dwordx4 v[6:7], v[2:5], off offset:2064
	s_branch .LBB0_16

;     __device__ __forceinline__ int tid_() const { return wave * 64 + lane_id(); }
; #define HG_BAR() do { asm volatile("s_waitcnt lgkmcnt(0)" ::: "memory"); __builtin_amdgcn_s_barrier(); asm volatile("" ::: "memory"); } while (0)
; __device__ __forceinline__ void phase_mixers(Frame& F, int layer, int qslot) {
;     ...
;         if (F.tid_() == 0) F.MISC[4] = __hip_atomic_fetch_add(head, 1u, __ATOMIC_RELAXED, __HIP_MEMORY_SCOPE_AGENT);
;         HG_BAR();
;         int u = (int)F.MISC[4];
;         HG_BAR();
;         if (u >= U_TOTAL) break;
;         if (u >= U0_HGS && u < U0_POOL) u = u < U0_HGS + sb::NUNITS ? u + U_HG_S : u - sb::NUNITS;
;         if (u < U0_ATT) { const bool smp = u >= U0_HGS; const int x = smp ? u - U0_HGS : u; hg::chain(F, layer, smp, x >> 3, x & 7); }
;         else if (u < U0_POOL) { const int x = u - U0_ATT; if (x < sb::NU_P) sb::block_unit<1>(F, layer, x); else sb::block_unit<4>(F, layer, x - sb::NU_P); }
;         else pl::unit(F, layer, u - U0_POOL);
.LBB0_563:
	s_or_b64 exec, exec, s[8:9]
	v_readlane_b32 s8, v241, 48
	s_waitcnt lgkmcnt(0)
	s_barrier
	s_nop 0
	v_mov_b32_e32 v0, s8
	ds_read_b32 v0, v0
	s_waitcnt lgkmcnt(0)
	s_barrier
	s_movk_i32 s8, 0x65f
	s_waitcnt lgkmcnt(0)
	v_cmp_lt_i32_e32 vcc, s8, v0
	v_readfirstlane_b32 s13, v0
	s_mov_b64 s[8:9], -1
	s_cbranch_vccnz .LBB0_558
	s_cmpk_lt_u32 s13, 64
	s_cselect_b32 s100, 1, s100
	s_sub_i32 s8, s13, 64
	s_cmpk_lt_i32 s13, 0x2c0
	s_movk_i32 s9, 0xfd80
	s_cselect_b32 s9, 0x100, s9
	s_cmpk_lt_u32 s8, 0x380
	s_cselect_b32 s12, s9, 0
	s_add_i32 s12, s12, s13
	s_cmpk_gt_i32 s12, 0x13f
	s_mov_b64 s[8:9], -1
	s_cbranch_scc0 .LBB0_750
	s_cmpk_gt_u32 s12, 0x3bf
	s_cbranch_scc0 .LBB0_683
	v_mov_b32_e32 v0, v173
	s_add_i32 s15, s12, 0xfffffc40
	s_cmpk_gt_u32 s15, 0x21f
	v_mbcnt_lo_u32_b32 v0, -1, v0
	v_mbcnt_hi_u32_b32 v0, -1, v0
	v_readlane_b32 s8, v241, 21
	s_cselect_b64 s[56:57], -1, 0
	s_cmpk_lt_u32 s15, 0x220
	v_add_u32_e32 v40, s8, v0
	s_cselect_b64 s[8:9], -1, 0
	s_mov_b64 s[26:27], -1
	s_and_b64 vcc, exec, s[56:57]
	s_cbranch_vccnz .LBB0_570
	s_lshr_b32 s14, s15, 2
	s_mul_i32 s15, s15, 0xf0f1
	s_lshr_b32 s20, s15, 22
	s_mul_i32 s15, s20, 0xffffffef
	s_add_i32 s15, s15, s14
	s_lshl_b32 s14, s15, 7
	s_movk_i32 s24, 0x810
	s_cbranch_execz .LBB0_571

; #define GAS __attribute__((address_space(1)))
; __device__ __forceinline__ unsigned cvt_pk_bf16(float lo, float hi) { const f32x2 v = {lo, hi}; return __builtin_bit_cast(unsigned, __builtin_convertvector(v, bf16n2)); }
;     __device__ __forceinline__ int lane_() const { return lane_id(); }
; #define F_w_in F.in(8)
; __device__ __forceinline__ void p0_transpose_item(const GAS float* W, int K, int N, GAS bf16* WT, int item, int lane) {
;     const int nblk = N / 64, kb = item / nblk, nb = item - kb * nblk, r = lane >> 4, c4 = lane & 15;
;     const GAS float* src = W + (size_t)(64 * kb + 16 * r) * N + 64 * nb + 4 * c4;
;     f32x4 v[16];
; #pragma unroll
;     for (int i = 0; i < 16; ++i) v[i] = __builtin_nontemporal_load((const GAS f32x4*)(src + (size_t)i * N));
;     GAS bf16* dst = WT + (size_t)(64 * nb + 4 * c4) * K + 64 * kb + 16 * r;
; #pragma unroll
;     for (int j = 0; j < 4; ++j) { v4u a, b;
;         a.x = cvt_pk_bf16(v[0][j], v[1][j]); a.y = cvt_pk_bf16(v[2][j], v[3][j]); a.z = cvt_pk_bf16(v[4][j], v[5][j]); a.w = cvt_pk_bf16(v[6][j], v[7][j]);
;         b.x = cvt_pk_bf16(v[8][j], v[9][j]); b.y = cvt_pk_bf16(v[10][j], v[11][j]); b.z = cvt_pk_bf16(v[12][j], v[13][j]); b.w = cvt_pk_bf16(v[14][j], v[15][j]);
;         *(GAS v4u*)(dst + (size_t)j * K) = a; *(GAS v4u*)(dst + (size_t)j * K + 8) = b; }
; }
; __device__ __forceinline__ void phase_prologue(Frame& F) {
;     ...
;     for (int it = gw; it < NITEMS; it += NGW) {
;         int r = it;
;         if (r < 2 * I_IN) { const int l = r / I_IN; p0_transpose_item(F_w_in + (size_t)l * D * NPROJ, D, NPROJ, win_t + (size_t)l * NPROJ * D, r % I_IN, F.lane_()); continue; } r -= 2 * I_IN;
;         if (r < 6 * I_SQ) { const int m = r / I_SQ; p0_transpose_item(F_w_branch + (size_t)m * D * D, D, D, wbr_t + (size_t)m * D * D, r % I_SQ, F.lane_()); continue; } r -= 6 * I_SQ;
;         if (r < 2 * I_SQ) { const int m = r / I_SQ; p0_transpose_item(F_w_out + (size_t)m * D * D, D, D, wout_t + (size_t)m * D * D, r % I_SQ, F.lane_()); continue; } r -= 2 * I_SQ;
;         { const int m = r / I_PL; p0_transpose_item(F_w_pool + (size_t)m * 65536, 256, 256, wpool_t + (size_t)m * 65536, r % I_PL, F.lane_()); }
;     }
.LBB0_881:
	v_readlane_b32 s8, v240, 7
	s_cmp_lg_u32 s8, 0
	s_cbranch_scc1 .Ldt_done
	s_cmp_lg_u32 s100, 0
	s_cbranch_scc1 .Ldt_done
	v_mbcnt_lo_u32_b32 v182, -1, 0
	v_mbcnt_hi_u32_b32 v182, -1, v182
	v_mov_b32_e32 v188, 0x27d40
	v_mov_b32_e32 v190, s18
	ds_read_b64 v[188:189], v188
	ds_read_b64 v[190:191], v190
	v_lshrrev_b32_e32 v183, 4, v182
	v_and_b32_e32 v184, 15, v182
	v_mul_u32_u24_e32 v185, 0xd0000, v183
	v_lshl_add_u32 v185, v184, 4, v185
	v_lshlrev_b32_e32 v186, 13, v184
	v_lshl_add_u32 v186, v183, 5, v186
	v_add_u32_e32 v187, 0x1000, v186
	s_waitcnt lgkmcnt(0)
	v_readfirstlane_b32 s16, v188
	v_readfirstlane_b32 s17, v189
	v_readfirstlane_b32 s14, v190
	v_readfirstlane_b32 s15, v191
	s_add_u32 s16, s16, 0x3400000
	s_addc_u32 s17, s17, 0
	s_add_u32 s64, s14, 0x1c00000
	s_addc_u32 s65, s15, 0
	s_add_u32 s14, s14, 0x8000
	s_addc_u32 s15, s15, 0
.Ldt_next:
	v_cmp_eq_u32_e32 vcc, 0, v182
	s_and_saveexec_b64 s[12:13], vcc
	global_atomic_add v200, v173, v213, s[14:15] sc0
	s_or_b64 exec, exec, s[12:13]
	s_waitcnt vmcnt(0)
	v_readfirstlane_b32 s61, v200
	s_cmpk_gt_u32 s61, 0xcff
	s_cbranch_scc1 .Ldt_done
	s_mul_i32 s8, s61, 0x4ec5
	s_lshr_b32 s8, s8, 22
	s_mul_i32 s9, s8, 0xd0
	s_sub_u32 s9, s61, s9
	s_mul_i32 s20, s8, 0x340000
	s_lshl_b32 s32, s9, 8
	s_add_u32 s20, s20, s32
	s_add_u32 s66, s16, s20
	s_addc_u32 s67, s17, 0
	global_load_dwordx4 v[80:83], v185, s[66:67] nt
	s_add_u32 s66, s66, 0xd000
	s_addc_u32 s67, s67, 0
	global_load_dwordx4 v[84:87], v185, s[66:67] nt
	s_add_u32 s66, s66, 0xd000
	s_addc_u32 s67, s67, 0
	global_load_dwordx4 v[88:91], v185, s[66:67] nt
	s_add_u32 s66, s66, 0xd000
	s_addc_u32 s67, s67, 0
	global_load_dwordx4 v[92:95], v185, s[66:67] nt
	s_add_u32 s66, s66, 0xd000
	s_addc_u32 s67, s67, 0
	global_load_dwordx4 v[96:99], v185, s[66:67] nt
	s_add_u32 s66, s66, 0xd000
	s_addc_u32 s67, s67, 0
	global_load_dwordx4 v[100:103], v185, s[66:67] nt
	s_add_u32 s66, s66, 0xd000
	s_addc_u32 s67, s67, 0
	global_load_dwordx4 v[104:107], v185, s[66:67] nt
	s_add_u32 s66, s66, 0xd000
	s_addc_u32 s67, s67, 0
	global_load_dwordx4 v[108:111], v185, s[66:67] nt
	s_add_u32 s66, s66, 0xd000
	s_addc_u32 s67, s67, 0
	global_load_dwordx4 v[128:131], v185, s[66:67] nt
	s_add_u32 s66, s66, 0xd000
	s_addc_u32 s67, s67, 0
	global_load_dwordx4 v[132:135], v185, s[66:67] nt
	s_add_u32 s66, s66, 0xd000
	s_addc_u32 s67, s67, 0
	global_load_dwordx4 v[136:139], v185, s[66:67] nt
	s_add_u32 s66, s66, 0xd000
	s_addc_u32 s67, s67, 0
	global_load_dwordx4 v[140:143], v185, s[66:67] nt
	s_add_u32 s66, s66, 0xd000
	s_addc_u32 s67, s67, 0
	global_load_dwordx4 v[144:147], v185, s[66:67] nt
	s_add_u32 s66, s66, 0xd000
	s_addc_u32 s67, s67, 0
	global_load_dwordx4 v[152:155], v185, s[66:67] nt
	s_add_u32 s66, s66, 0xd000
	s_addc_u32 s67, s67, 0
	global_load_dwordx4 v[156:159], v185, s[66:67] nt
	s_add_u32 s66, s66, 0xd000
	s_addc_u32 s67, s67, 0
	global_load_dwordx4 v[160:163], v185, s[66:67] nt
	s_lshl_b32 s20, s9, 17
	s_lshl_b32 s32, s8, 7
	s_add_u32 s20, s20, s32
	s_add_u32 s68, s64, s20
	s_addc_u32 s69, s65, 0
	s_waitcnt vmcnt(0)
	v_cvt_pk_bf16_f32 v164, v80, v84
	v_cvt_pk_bf16_f32 v165, v88, v92
	v_cvt_pk_bf16_f32 v166, v96, v100
	v_cvt_pk_bf16_f32 v167, v104, v108
	v_cvt_pk_bf16_f32 v168, v128, v132
	v_cvt_pk_bf16_f32 v169, v136, v140
	v_cvt_pk_bf16_f32 v170, v144, v152
	v_cvt_pk_bf16_f32 v171, v156, v160
	global_store_dwordx4 v186, v[164:167], s[68:69]
	global_store_dwordx4 v186, v[168:171], s[68:69] offset:16
	v_cvt_pk_bf16_f32 v192, v81, v85
	v_cvt_pk_bf16_f32 v193, v89, v93
	v_cvt_pk_bf16_f32 v194, v97, v101
	v_cvt_pk_bf16_f32 v195, v105, v109
	v_cvt_pk_bf16_f32 v196, v129, v133
	v_cvt_pk_bf16_f32 v197, v137, v141
	v_cvt_pk_bf16_f32 v198, v145, v153
	v_cvt_pk_bf16_f32 v199, v157, v161
	global_store_dwordx4 v186, v[192:195], s[68:69] offset:2048
	global_store_dwordx4 v186, v[196:199], s[68:69] offset:2064
	v_cvt_pk_bf16_f32 v164, v82, v86
	v_cvt_pk_bf16_f32 v165, v90, v94
	v_cvt_pk_bf16_f32 v166, v98, v102
	v_cvt_pk_bf16_f32 v167, v106, v110
	v_cvt_pk_bf16_f32 v168, v130, v134
	v_cvt_pk_bf16_f32 v169, v138, v142
	v_cvt_pk_bf16_f32 v170, v146, v154
	v_cvt_pk_bf16_f32 v171, v158, v162
	global_store_dwordx4 v187, v[164:167], s[68:69]
	global_store_dwordx4 v187, v[168:171], s[68:69] offset:16
	v_cvt_pk_bf16_f32 v192, v83, v87
	v_cvt_pk_bf16_f32 v193, v91, v95
	v_cvt_pk_bf16_f32 v194, v99, v103
	v_cvt_pk_bf16_f32 v195, v107, v111
	v_cvt_pk_bf16_f32 v196, v131, v135
	v_cvt_pk_bf16_f32 v197, v139, v143
	v_cvt_pk_bf16_f32 v198, v147, v155
	v_cvt_pk_bf16_f32 v199, v159, v163
	global_store_dwordx4 v187, v[192:195], s[68:69] offset:2048
	global_store_dwordx4 v187, v[196:199], s[68:69] offset:2064
	s_branch .Ldt_next
.Ldt_done:
	s_mov_b32 s100, 0
	v_readlane_b32 s8, v240, 7
	v_readlane_b32 s64, v241, 59
	s_add_i32 s14, s8, 4
	v_readlane_b32 s65, v241, 60
	s_cmp_ge_i32 s14, s65
	s_cbranch_scc1 .LBB0_894
	s_waitcnt vmcnt(0)
	v_readlane_b32 s72, v241, 63
	s_and_b64 vcc, exec, s[54:55]
	v_readlane_b32 s66, v241, 61
	v_readlane_b32 s73, v240, 0
	s_waitcnt vmcnt(0) lgkmcnt(0)
	s_barrier
	v_readlane_b32 s67, v241, 62
	s_cbranch_vccnz .LBB0_928
	v_mov_b32_e32 v0, v173
	s_nop 0
	v_mbcnt_lo_u32_b32 v0, -1, v0
	v_mbcnt_hi_u32_b32 v0, -1, v0
	v_cmp_eq_u32_e32 vcc, 0, v0
	s_and_saveexec_b64 s[8:9], vcc
	s_cbranch_execz .LBB0_927
	v_readlane_b32 s12, v243, 2
	s_waitcnt vmcnt(0) expcnt(0) lgkmcnt(0)
	v_readlane_b32 s26, v240, 1
	v_mov_b32_e32 v0, s12
	ds_read_b32 v2, v0
	ds_read_b32 v1, v0 offset:4
	v_readlane_b32 s27, v240, 2
	s_waitcnt lgkmcnt(1)
	v_cmp_ne_u32_e32 vcc, 0, v2
	s_cbranch_vccnz .LBB0_898
	v_readlane_b32 s16, v243, 0
	v_readlane_b32 s17, v243, 1
	s_load_dwordx2 s[12:13], s[16:17], 0x4
	s_mov_b32 s20, 1
	s_waitcnt lgkmcnt(0)
	s_mul_i32 s15, s12, s2
	s_mul_i32 s15, s15, s13
	s_branch .LBB0_887
